# EpiRes second x-load batch: full vmcnt drain before the second half instead of counted waits (keeps load and store bursts separate)
# baseline (speedup 1.0000x reference)
; #define LAS __attribute__((address_space(3)))
; __device__ __forceinline__ unsigned cvt_pk_bf16(float lo, float hi) { const cvt_f32x2_t v = {lo, hi}; const cvt_bf16x2_t b = __builtin_convertvector(v, cvt_bf16x2_t); return __builtin_bit_cast(unsigned, b); }
; __device__ __forceinline__ float sq4(f32x4 v) { return (v[0] * v[0] + v[1] * v[1]) + (v[2] * v[2] + v[3] * v[3]); }
;     __device__ __forceinline__ void operator()(const f32x4 (&acc)[2][2][4][2], const Unit& u, int wr, int wc, int fr, int fq) const {
;     ...
;             for (int m = 0; m < 4; ++m) { const size_t off = (size_t)(u.pm * 256 + ai * 128 + wr * 64 + m * 16 + fr) * DM + col0;
; #pragma unroll
;                 for (int bj = 0; bj < 2; ++bj)
; #pragma unroll
;                     for (int n = 0; n < 2; ++n) xr[m][bj][n] = *(const f32x4*)(xin + off + 128 * bj + 4 * n); }
;             asm volatile("" ::: "memory");
; #pragma unroll
;             for (int m = 0; m < 4; ++m) {
;                 const int row = u.pm * 256 + ai * 128 + wr * 64 + m * 16 + fr;
;                 const size_t off = (size_t)row * DM + col0;
;                 float ss = 0.f;
; #pragma unroll
;                 for (int bj = 0; bj < 2; ++bj) {
;                     const f32x4 xo0 = xr[m][bj][0] + *(const LAS f32x4*)(gtp + 128 * bj) * acc[ai][bj][m][0], xo1 = xr[m][bj][1] + *(const LAS f32x4*)(gtp + 128 * bj + 4) * acc[ai][bj][m][1];
;                     *(f32x4*)(xout + off + 128 * bj) = xo0; *(f32x4*)(xout + off + 128 * bj + 4) = xo1;
;                     if (gmn) { ss += sq4(xo0) + sq4(xo1); const f32x4 a = xo0 * *(const LAS f32x4*)(gmp + 128 * bj), c = xo1 * *(const LAS f32x4*)(gmp + 128 * bj + 4);
;                         u32x4 w; w.x = cvt_pk_bf16(a[0], a[1]); w.y = cvt_pk_bf16(a[2], a[3]); w.z = cvt_pk_bf16(c[0], c[1]); w.w = cvt_pk_bf16(c[2], c[3]); *(u32x4*)(AX + off + 128 * bj) = w; }
;                 }
;                 if (gmn) { ss += __shfl_xor(ss, 16); ss += __shfl_xor(ss, 32); if (fq == 0) statx[(size_t)row * 16 + u.pn * 4 + wc] = ss; }
.LBB0_240:
	v_add_u32_e32 v134, 0x80, v226
	v_ashrrev_i32_e32 v135, 31, v134
	s_waitcnt lgkmcnt(0)
	v_lshlrev_b64 v[64:65], 12, v[134:135]
	v_add_u32_e32 v132, 0x90, v226
	v_lshl_add_u64 v[64:65], v[228:229], 0, v[64:65]
	v_ashrrev_i32_e32 v133, 31, v132
	global_load_dwordx4 v[136:139], v[64:65], off offset:16
	global_load_dwordx4 v[140:143], v[64:65], off
	global_load_dwordx4 v[120:123], v[64:65], off offset:528
	global_load_dwordx4 v[124:127], v[64:65], off offset:512
	v_lshlrev_b64 v[64:65], 12, v[132:133]
	v_add_u32_e32 v130, 0xa0, v226
	v_lshl_add_u64 v[64:65], v[228:229], 0, v[64:65]
	v_ashrrev_i32_e32 v131, 31, v130
	global_load_dwordx4 v[112:115], v[64:65], off offset:16
	global_load_dwordx4 v[116:119], v[64:65], off
	global_load_dwordx4 v[104:107], v[64:65], off offset:528
	global_load_dwordx4 v[108:111], v[64:65], off offset:512
	v_lshlrev_b64 v[64:65], 12, v[130:131]
	v_add_u32_e32 v128, 0xb0, v226
	v_lshl_add_u64 v[64:65], v[228:229], 0, v[64:65]
	v_ashrrev_i32_e32 v129, 31, v128
	global_load_dwordx4 v[96:99], v[64:65], off offset:16
	global_load_dwordx4 v[100:103], v[64:65], off
	global_load_dwordx4 v[88:91], v[64:65], off offset:528
	global_load_dwordx4 v[92:95], v[64:65], off offset:512
	v_lshlrev_b64 v[64:65], 12, v[128:129]
	v_lshl_add_u64 v[68:69], v[228:229], 0, v[64:65]
	global_load_dwordx4 v[72:75], v[68:69], off offset:16
	global_load_dwordx4 v[80:83], v[68:69], off
	global_load_dwordx4 v[64:67], v[68:69], off offset:528
	s_nop 0
	global_load_dwordx4 v[68:71], v[68:69], off offset:512
	v_lshlrev_b64 v[76:77], 10, v[134:135]
	v_lshl_add_u64 v[144:145], v[76:77], 0, v[224:225]
	ds_read_b128 v[84:87], v249
	ds_read_b128 v[76:79], v249 offset:16
	s_and_b64 vcc, exec, s[46:47]
	s_waitcnt vmcnt(0) lgkmcnt(0)
	v_pk_fma_f32 v[58:59], v[58:59], v[78:79], v[138:139]
	s_waitcnt vmcnt(14)
	v_pk_fma_f32 v[62:63], v[62:63], v[86:87], v[142:143]
	v_pk_fma_f32 v[60:61], v[60:61], v[84:85], v[140:141]
	v_pk_fma_f32 v[56:57], v[56:57], v[76:77], v[136:137]
	v_lshl_add_u64 v[136:137], v[144:145], 2, s[20:21]
	v_lshl_add_u32 v136, v144, 2, v246
	v_mov_b32_e32 v140, 0
	v_lshl_add_u64 v[138:139], v[144:145], 1, s[16:17]
	v_lshl_add_u64 v[138:139], v[204:205], 0, v[138:139]
	ds_write_b128 v208, v[60:63]
	ds_write_b128 v208, v[56:59] offset:16
	ds_read_b128 v[216:219], v210
	ds_read_b128 v[220:223], v210 offset:1152
	s_waitcnt lgkmcnt(0)
	global_store_dwordx4 v136, v[216:219], s[20:21]
	global_store_dwordx4 v136, v[220:223], s[100:101]
	s_cbranch_vccnz .LBB0_242
	v_mov_b32_e32 v142, v61
	v_mov_b32_e32 v143, v57
	v_mov_b32_e32 v140, v60
	v_mov_b32_e32 v141, v56
	v_pk_mul_f32 v[142:143], v[142:143], v[142:143]
	v_mov_b32_e32 v144, v63
	v_mov_b32_e32 v145, v59
	v_pk_fma_f32 v[140:141], v[140:141], v[140:141], v[142:143]
	v_mov_b32_e32 v142, v62
	v_mov_b32_e32 v143, v58
	v_pk_mul_f32 v[144:145], v[144:145], v[144:145]
	s_nop 0
	v_pk_fma_f32 v[142:143], v[142:143], v[142:143], v[144:145]
	s_nop 0
	v_pk_add_f32 v[140:141], v[140:141], v[142:143]
	ds_read_b128 v[142:145], v192
	ds_read_b128 v[146:149], v192 offset:16
	v_add_f32_e32 v140, v140, v141
	s_waitcnt lgkmcnt(1)
	v_pk_mul_f32 v[62:63], v[62:63], v[144:145]
	v_pk_mul_f32 v[60:61], v[60:61], v[142:143]
	s_waitcnt lgkmcnt(0)
	v_pk_mul_f32 v[142:143], v[58:59], v[148:149]
	v_pk_mul_f32 v[58:59], v[56:57], v[146:147]
	v_cvt_pk_bf16_f32 v56, v60, v61
	v_cvt_pk_bf16_f32 v57, v62, v63
	v_cvt_pk_bf16_f32 v58, v58, v59
	v_cvt_pk_bf16_f32 v59, v142, v143
	ds_bpermute_b32 v56, v206, v56
	ds_bpermute_b32 v57, v206, v57
	ds_bpermute_b32 v58, v206, v58
	ds_bpermute_b32 v59, v206, v59
	s_waitcnt lgkmcnt(0)
	global_store_dwordx4 v[138:139], v[56:59], off

; __device__ __forceinline__ unsigned cvt_pk_bf16(float lo, float hi) { const cvt_f32x2_t v = {lo, hi}; const cvt_bf16x2_t b = __builtin_convertvector(v, cvt_bf16x2_t); return __builtin_bit_cast(unsigned, b); }
;     __device__ __forceinline__ void operator()(const f32x4 (&acc)[2][2][4][2], const Unit& u, int wr, int wc, int fr, int fq) const {
;     ...
;         for (int ai = 0; ai < 2; ++ai)
; #pragma unroll
;             for (int m = 0; m < 4; ++m) {
;                 const int row = u.pm * 256 + ai * 128 + wr * 64 + m * 16 + fr;
;                 const float rs = rsl[ai * 128 + wr * 64 + m * 16 + fr];
; #pragma unroll
;                 for (int bj = 0; bj < 2; ++bj) {
;                     f32x4 a = acc[ai][bj][m][0] * rs + sw[bj][0], c = acc[ai][bj][m][1] * rs + sw[bj][1];
; #pragma unroll
;                     for (int e = 0; e < 4; ++e) { a[e] = fmaxf(a[e], 0.f); a[e] *= a[e]; c[e] = fmaxf(c[e], 0.f); c[e] *= c[e]; }
;                     u32x4 w; w.x = cvt_pk_bf16(a[0], a[1]); w.y = cvt_pk_bf16(a[2], a[3]); w.z = cvt_pk_bf16(c[0], c[1]); w.w = cvt_pk_bf16(c[2], c[3]);
;                     *(u32x4*)(H + (size_t)row * DFF + col0 + 128 * bj) = w;
;                 }
.LBB0_292:
	s_or_b64 exec, exec, s[44:45]
	v_lshlrev_b32_e32 v163, 2, v154
	s_waitcnt lgkmcnt(0)
	s_barrier
	v_add_u32_e32 v162, s76, v163
	ds_read2_b32 v[164:165], v162 offset1:16
	s_add_i32 s21, s21, s63
	v_add_u32_e32 v154, s21, v154
	v_add_u32_e32 v154, v154, v224
	v_ashrrev_i32_e32 v155, 31, v154
	v_lshlrev_b64 v[166:167], 13, v[154:155]
	s_waitcnt vmcnt(0) lgkmcnt(0)
	v_pk_fma_f32 v[142:143], v[142:143], v[164:165], v[134:135] op_sel_hi:[1,0,1]
	v_pk_fma_f32 v[140:141], v[140:141], v[164:165], v[132:133] op_sel_hi:[1,0,1]
	v_pk_fma_f32 v[136:137], v[136:137], v[164:165], v[128:129] op_sel_hi:[1,0,1]
	v_pk_fma_f32 v[138:139], v[138:139], v[164:165], v[130:131] op_sel_hi:[1,0,1]
	v_max_f32_e32 v140, 0, v140
	v_max_f32_e32 v136, 0, v136
	v_max_f32_e32 v141, 0, v141
	v_max_f32_e32 v137, 0, v137
	v_max_f32_e32 v142, 0, v142
	v_max_f32_e32 v143, 0, v143
	v_pk_mul_f32 v[140:141], v[140:141], v[140:141]
	v_pk_mul_f32 v[136:137], v[136:137], v[136:137]
	v_max_f32_e32 v138, 0, v138
	v_pk_mul_f32 v[142:143], v[142:143], v[142:143]
	v_max_f32_e32 v139, 0, v139
	v_pk_mul_f32 v[168:169], v[138:139], v[138:139]
	v_cvt_pk_bf16_f32 v138, v140, v141
	v_cvt_pk_bf16_f32 v139, v142, v143
	v_cvt_pk_bf16_f32 v140, v136, v137
	v_lshl_add_u64 v[142:143], s[8:9], 0, v[166:167]
	v_add_u32_e32 v156, v156, v227
	v_lshlrev_b64 v[136:137], 1, v[156:157]
	v_pk_fma_f32 v[112:113], v[112:113], v[164:165], v[120:121] op_sel_hi:[1,0,1]
	v_cvt_pk_bf16_f32 v141, v168, v169
	v_lshl_add_u64 v[142:143], v[142:143], 0, v[136:137]
	v_pk_fma_f32 v[118:119], v[118:119], v[164:165], v[126:127] op_sel_hi:[1,0,1]
	v_pk_fma_f32 v[116:117], v[116:117], v[164:165], v[124:125] op_sel_hi:[1,0,1]
	v_pk_fma_f32 v[114:115], v[114:115], v[164:165], v[122:123] op_sel_hi:[1,0,1]
	v_max_f32_e32 v112, 0, v112
	v_max_f32_e32 v113, 0, v113
	ds_bpermute_b32 v228, v226, v138
	ds_bpermute_b32 v229, v226, v139
	ds_bpermute_b32 v230, v226, v140
	ds_bpermute_b32 v231, v226, v141
	v_max_f32_e32 v116, 0, v116
	v_max_f32_e32 v117, 0, v117
	v_pk_mul_f32 v[138:139], v[112:113], v[112:113]
	v_max_f32_e32 v112, 0, v118
	v_max_f32_e32 v114, 0, v114
	v_max_f32_e32 v113, 0, v119
	v_max_f32_e32 v115, 0, v115
	v_pk_mul_f32 v[116:117], v[116:117], v[116:117]
	v_pk_mul_f32 v[118:119], v[112:113], v[112:113]
	v_pk_mul_f32 v[140:141], v[114:115], v[114:115]
	v_cvt_pk_bf16_f32 v112, v116, v117
	v_cvt_pk_bf16_f32 v113, v118, v119
	v_cvt_pk_bf16_f32 v114, v138, v139
	v_cvt_pk_bf16_f32 v115, v140, v141
	s_waitcnt lgkmcnt(0)
	global_store_dwordx4 v[142:143], v[228:231], off
	ds_bpermute_b32 v232, v226, v112
	ds_bpermute_b32 v233, v226, v113
	ds_bpermute_b32 v234, v226, v114
	ds_bpermute_b32 v235, v226, v115
	s_andn2_b64 vcc, exec, s[42:43]
	s_mov_b64 s[42:43], -1
	v_mov_b32_e32 v114, v165
	v_add_u32_e32 v112, 16, v154
	v_pk_fma_f32 v[108:109], v[108:109], v[114:115], v[132:133] op_sel_hi:[1,0,1]
	v_pk_fma_f32 v[104:105], v[104:105], v[114:115], v[128:129] op_sel_hi:[1,0,1]
	v_ashrrev_i32_e32 v113, 31, v112
	v_pk_fma_f32 v[110:111], v[110:111], v[114:115], v[134:135] op_sel_hi:[1,0,1]
	v_pk_fma_f32 v[106:107], v[106:107], v[114:115], v[130:131] op_sel_hi:[1,0,1]
	v_max_f32_e32 v108, 0, v108
	v_max_f32_e32 v104, 0, v104
	v_max_f32_e32 v109, 0, v109
	v_max_f32_e32 v105, 0, v105
	v_lshlrev_b64 v[112:113], 13, v[112:113]
	v_pk_mul_f32 v[108:109], v[108:109], v[108:109]
	v_pk_mul_f32 v[116:117], v[104:105], v[104:105]
	v_max_f32_e32 v104, 0, v110
	v_max_f32_e32 v106, 0, v106
	v_max_f32_e32 v105, 0, v111
	v_max_f32_e32 v107, 0, v107
	v_pk_mul_f32 v[110:111], v[104:105], v[104:105]
	v_pk_mul_f32 v[118:119], v[106:107], v[106:107]
	v_cvt_pk_bf16_f32 v104, v108, v109
	v_lshl_add_u64 v[108:109], s[8:9], 0, v[112:113]
	v_pk_fma_f32 v[100:101], v[100:101], v[114:115], v[124:125] op_sel_hi:[1,0,1]
	v_pk_fma_f32 v[96:97], v[96:97], v[114:115], v[120:121] op_sel_hi:[1,0,1]
	v_cvt_pk_bf16_f32 v105, v110, v111
	v_cvt_pk_bf16_f32 v106, v116, v117
	v_cvt_pk_bf16_f32 v107, v118, v119
	v_lshl_add_u64 v[108:109], v[108:109], 0, v[136:137]
	v_pk_fma_f32 v[102:103], v[102:103], v[114:115], v[126:127] op_sel_hi:[1,0,1]
	v_max_f32_e32 v100, 0, v100
	v_max_f32_e32 v96, 0, v96
	v_max_f32_e32 v101, 0, v101
	v_max_f32_e32 v97, 0, v97
	s_waitcnt lgkmcnt(0)
	global_store_dwordx4 v[142:143], v[232:235], off offset:256
	ds_bpermute_b32 v236, v226, v104
	ds_bpermute_b32 v237, v226, v105
	ds_bpermute_b32 v238, v226, v106
	ds_bpermute_b32 v239, v226, v107
	v_pk_mul_f32 v[100:101], v[100:101], v[100:101]
	v_pk_fma_f32 v[98:99], v[98:99], v[114:115], v[122:123] op_sel_hi:[1,0,1]
	v_pk_mul_f32 v[104:105], v[96:97], v[96:97]
	v_max_f32_e32 v96, 0, v102
	v_max_f32_e32 v97, 0, v103
	v_pk_mul_f32 v[102:103], v[96:97], v[96:97]
	v_cvt_pk_bf16_f32 v96, v100, v101
	ds_read2_b32 v[100:101], v162 offset0:32 offset1:48
	v_max_f32_e32 v98, 0, v98
	v_max_f32_e32 v99, 0, v99
	v_pk_mul_f32 v[106:107], v[98:99], v[98:99]
	v_cvt_pk_bf16_f32 v97, v102, v103
	v_cvt_pk_bf16_f32 v98, v104, v105
	v_cvt_pk_bf16_f32 v99, v106, v107
	s_waitcnt lgkmcnt(0)
	global_store_dwordx4 v[108:109], v[236:239], off
	ds_bpermute_b32 v228, v226, v96
	ds_bpermute_b32 v229, v226, v97
	ds_bpermute_b32 v230, v226, v98
	ds_bpermute_b32 v231, v226, v99
	s_waitcnt lgkmcnt(0)
; __device__ __forceinline__ unsigned cvt_pk_bf16(float lo, float hi) { const cvt_f32x2_t v = {lo, hi}; const cvt_bf16x2_t b = __builtin_convertvector(v, cvt_bf16x2_t); return __builtin_bit_cast(unsigned, b); }
;     __device__ __forceinline__ void operator()(const f32x4 (&acc)[2][2][4][2], const Unit& u, int wr, int wc, int fr, int fq) const {
;     ...
;         for (int ai = 0; ai < 2; ++ai)
; #pragma unroll
;             for (int m = 0; m < 4; ++m) {
;                 const int row = u.pm * 256 + ai * 128 + wr * 64 + m * 16 + fr;
;                 const float rs = rsl[ai * 128 + wr * 64 + m * 16 + fr];
; #pragma unroll
;                 for (int bj = 0; bj < 2; ++bj) {
;                     f32x4 a = acc[ai][bj][m][0] * rs + sw[bj][0], c = acc[ai][bj][m][1] * rs + sw[bj][1];
; #pragma unroll
;                     for (int e = 0; e < 4; ++e) { a[e] = fmaxf(a[e], 0.f); a[e] *= a[e]; c[e] = fmaxf(c[e], 0.f); c[e] *= c[e]; }
;                     u32x4 w; w.x = cvt_pk_bf16(a[0], a[1]); w.y = cvt_pk_bf16(a[2], a[3]); w.z = cvt_pk_bf16(c[0], c[1]); w.w = cvt_pk_bf16(c[2], c[3]);
;                     *(u32x4*)(H + (size_t)row * DFF + col0 + 128 * bj) = w;
;                 }
	v_pk_fma_f32 v[92:93], v[92:93], v[100:101], v[132:133] op_sel_hi:[1,0,1]
	v_pk_fma_f32 v[88:89], v[88:89], v[100:101], v[128:129] op_sel_hi:[1,0,1]
	v_add_u32_e32 v96, 32, v154
	v_ashrrev_i32_e32 v97, 31, v96
	v_pk_fma_f32 v[94:95], v[94:95], v[100:101], v[134:135] op_sel_hi:[1,0,1]
	v_pk_fma_f32 v[90:91], v[90:91], v[100:101], v[130:131] op_sel_hi:[1,0,1]
	v_max_f32_e32 v92, 0, v92
	v_max_f32_e32 v88, 0, v88
	v_max_f32_e32 v93, 0, v93
	v_max_f32_e32 v89, 0, v89
	v_lshlrev_b64 v[96:97], 13, v[96:97]
	v_pk_mul_f32 v[92:93], v[92:93], v[92:93]
	v_pk_mul_f32 v[98:99], v[88:89], v[88:89]
	v_max_f32_e32 v88, 0, v94
	v_max_f32_e32 v90, 0, v90
	v_max_f32_e32 v89, 0, v95
	v_max_f32_e32 v91, 0, v91
	v_pk_mul_f32 v[94:95], v[88:89], v[88:89]
	v_pk_mul_f32 v[102:103], v[90:91], v[90:91]
	v_cvt_pk_bf16_f32 v88, v92, v93
	v_lshl_add_u64 v[92:93], s[8:9], 0, v[96:97]
	v_pk_fma_f32 v[80:81], v[80:81], v[100:101], v[120:121] op_sel_hi:[1,0,1]
	v_cvt_pk_bf16_f32 v89, v94, v95
	v_cvt_pk_bf16_f32 v90, v98, v99
	v_cvt_pk_bf16_f32 v91, v102, v103
	v_lshl_add_u64 v[92:93], v[92:93], 0, v[136:137]
	v_pk_fma_f32 v[86:87], v[86:87], v[100:101], v[126:127] op_sel_hi:[1,0,1]
	v_pk_fma_f32 v[84:85], v[84:85], v[100:101], v[124:125] op_sel_hi:[1,0,1]
	v_pk_fma_f32 v[82:83], v[82:83], v[100:101], v[122:123] op_sel_hi:[1,0,1]
	v_max_f32_e32 v80, 0, v80
	v_max_f32_e32 v81, 0, v81
	s_waitcnt lgkmcnt(0)
	global_store_dwordx4 v[108:109], v[228:231], off offset:256
	ds_bpermute_b32 v232, v226, v88
	ds_bpermute_b32 v233, v226, v89
	ds_bpermute_b32 v234, v226, v90
	ds_bpermute_b32 v235, v226, v91
	v_max_f32_e32 v84, 0, v84
	v_max_f32_e32 v85, 0, v85
	v_pk_mul_f32 v[88:89], v[80:81], v[80:81]
	v_max_f32_e32 v80, 0, v86
	v_max_f32_e32 v82, 0, v82
	v_max_f32_e32 v81, 0, v87
	v_max_f32_e32 v83, 0, v83
	v_pk_mul_f32 v[84:85], v[84:85], v[84:85]
	v_pk_mul_f32 v[86:87], v[80:81], v[80:81]
	v_pk_mul_f32 v[90:91], v[82:83], v[82:83]
	v_cvt_pk_bf16_f32 v80, v84, v85
	v_cvt_pk_bf16_f32 v81, v86, v87
	v_cvt_pk_bf16_f32 v82, v88, v89
	v_cvt_pk_bf16_f32 v83, v90, v91
	s_waitcnt lgkmcnt(0)
	global_store_dwordx4 v[92:93], v[232:235], off
	ds_bpermute_b32 v236, v226, v80
	ds_bpermute_b32 v237, v226, v81
	ds_bpermute_b32 v238, v226, v82
	ds_bpermute_b32 v239, v226, v83
	s_nop 1
	v_mov_b32_e32 v82, v101
	v_add_u32_e32 v80, 48, v154
	v_pk_fma_f32 v[76:77], v[76:77], v[82:83], v[132:133] op_sel_hi:[1,0,1]
	v_pk_fma_f32 v[72:73], v[72:73], v[82:83], v[128:129] op_sel_hi:[1,0,1]
	v_ashrrev_i32_e32 v81, 31, v80
	v_pk_fma_f32 v[78:79], v[78:79], v[82:83], v[134:135] op_sel_hi:[1,0,1]
	v_pk_fma_f32 v[74:75], v[74:75], v[82:83], v[130:131] op_sel_hi:[1,0,1]
	v_max_f32_e32 v76, 0, v76
	v_max_f32_e32 v72, 0, v72
	v_max_f32_e32 v77, 0, v77
	v_max_f32_e32 v73, 0, v73
	v_lshlrev_b64 v[80:81], 13, v[80:81]
	v_pk_mul_f32 v[76:77], v[76:77], v[76:77]
	v_pk_mul_f32 v[84:85], v[72:73], v[72:73]
	v_max_f32_e32 v72, 0, v78
	v_max_f32_e32 v74, 0, v74
	v_max_f32_e32 v73, 0, v79
	v_max_f32_e32 v75, 0, v75
	v_pk_mul_f32 v[78:79], v[72:73], v[72:73]
	v_pk_mul_f32 v[86:87], v[74:75], v[74:75]
	v_cvt_pk_bf16_f32 v72, v76, v77
	v_lshl_add_u64 v[76:77], s[8:9], 0, v[80:81]
	v_pk_fma_f32 v[64:65], v[64:65], v[82:83], v[120:121] op_sel_hi:[1,0,1]
	v_cvt_pk_bf16_f32 v73, v78, v79
	v_cvt_pk_bf16_f32 v74, v84, v85
	v_cvt_pk_bf16_f32 v75, v86, v87
	v_lshl_add_u64 v[76:77], v[76:77], 0, v[136:137]
	v_pk_fma_f32 v[70:71], v[70:71], v[82:83], v[126:127] op_sel_hi:[1,0,1]
	v_pk_fma_f32 v[68:69], v[68:69], v[82:83], v[124:125] op_sel_hi:[1,0,1]
	v_pk_fma_f32 v[66:67], v[66:67], v[82:83], v[122:123] op_sel_hi:[1,0,1]
	v_max_f32_e32 v64, 0, v64
	v_max_f32_e32 v65, 0, v65
	s_waitcnt lgkmcnt(0)
	global_store_dwordx4 v[92:93], v[236:239], off offset:256
	ds_bpermute_b32 v228, v226, v72
	ds_bpermute_b32 v229, v226, v73
	ds_bpermute_b32 v230, v226, v74
	ds_bpermute_b32 v231, v226, v75
	v_max_f32_e32 v68, 0, v68
	v_max_f32_e32 v69, 0, v69
	v_pk_mul_f32 v[72:73], v[64:65], v[64:65]
	v_max_f32_e32 v64, 0, v70
	v_max_f32_e32 v66, 0, v66
	v_max_f32_e32 v65, 0, v71
	v_max_f32_e32 v67, 0, v67
	v_pk_mul_f32 v[68:69], v[68:69], v[68:69]
	v_pk_mul_f32 v[70:71], v[64:65], v[64:65]
	v_pk_mul_f32 v[74:75], v[66:67], v[66:67]
	v_cvt_pk_bf16_f32 v64, v68, v69
	v_cvt_pk_bf16_f32 v65, v70, v71
	v_cvt_pk_bf16_f32 v66, v72, v73
	v_cvt_pk_bf16_f32 v67, v74, v75
	s_waitcnt lgkmcnt(0)
	global_store_dwordx4 v[76:77], v[228:231], off
	ds_bpermute_b32 v232, v226, v64
	ds_bpermute_b32 v233, v226, v65
	ds_bpermute_b32 v234, v226, v66
	ds_bpermute_b32 v235, v226, v67
	ds_read_b32 v68, v162 offset:704
	s_waitcnt lgkmcnt(0)
	v_pk_fma_f32 v[8:9], v[8:9], v[68:69], v[128:129] op_sel_hi:[1,0,1]
	v_add_u32_e32 v64, s77, v163
	ds_read_b32 v64, v64
	v_add_u32_e32 v66, 0x80, v154
	v_ashrrev_i32_e32 v67, 31, v66
	v_lshlrev_b64 v[66:67], 13, v[66:67]
	v_pk_fma_f32 v[16:17], v[16:17], v[68:69], v[132:133] op_sel_hi:[1,0,1]
	s_waitcnt lgkmcnt(0)
	v_pk_fma_f32 v[60:61], v[60:61], v[64:65], v[132:133] op_sel_hi:[1,0,1]
	v_pk_fma_f32 v[56:57], v[56:57], v[64:65], v[128:129] op_sel_hi:[1,0,1]
	v_pk_fma_f32 v[62:63], v[62:63], v[64:65], v[134:135] op_sel_hi:[1,0,1]
	v_pk_fma_f32 v[58:59], v[58:59], v[64:65], v[130:131] op_sel_hi:[1,0,1]
	v_max_f32_e32 v60, 0, v60
	v_max_f32_e32 v56, 0, v56
	v_max_f32_e32 v61, 0, v61
	v_max_f32_e32 v57, 0, v57
	v_pk_mul_f32 v[60:61], v[60:61], v[60:61]
	v_pk_mul_f32 v[70:71], v[56:57], v[56:57]
	v_max_f32_e32 v56, 0, v62
	v_max_f32_e32 v58, 0, v58
	v_max_f32_e32 v57, 0, v63
	v_max_f32_e32 v59, 0, v59
	v_pk_mul_f32 v[62:63], v[56:57], v[56:57]
	v_pk_mul_f32 v[72:73], v[58:59], v[58:59]
	v_cvt_pk_bf16_f32 v56, v60, v61
	v_lshl_add_u64 v[60:61], s[8:9], 0, v[66:67]
	v_pk_fma_f32 v[52:53], v[52:53], v[64:65], v[124:125] op_sel_hi:[1,0,1]
	v_pk_fma_f32 v[44:45], v[44:45], v[64:65], v[120:121] op_sel_hi:[1,0,1]
	v_cvt_pk_bf16_f32 v57, v62, v63
	v_cvt_pk_bf16_f32 v58, v70, v71
	v_cvt_pk_bf16_f32 v59, v72, v73
	v_lshl_add_u64 v[60:61], v[60:61], 0, v[136:137]
	v_pk_fma_f32 v[54:55], v[54:55], v[64:65], v[126:127] op_sel_hi:[1,0,1]
	v_max_f32_e32 v52, 0, v52
	v_max_f32_e32 v44, 0, v44
	v_max_f32_e32 v53, 0, v53
	v_max_f32_e32 v45, 0, v45
	s_waitcnt lgkmcnt(0)
; __device__ __forceinline__ unsigned cvt_pk_bf16(float lo, float hi) { const cvt_f32x2_t v = {lo, hi}; const cvt_bf16x2_t b = __builtin_convertvector(v, cvt_bf16x2_t); return __builtin_bit_cast(unsigned, b); }
;     __device__ __forceinline__ void operator()(const f32x4 (&acc)[2][2][4][2], const Unit& u, int wr, int wc, int fr, int fq) const {
;     ...
;         for (int ai = 0; ai < 2; ++ai)
; #pragma unroll
;             for (int m = 0; m < 4; ++m) {
;                 const int row = u.pm * 256 + ai * 128 + wr * 64 + m * 16 + fr;
;                 const float rs = rsl[ai * 128 + wr * 64 + m * 16 + fr];
; #pragma unroll
;                 for (int bj = 0; bj < 2; ++bj) {
;                     f32x4 a = acc[ai][bj][m][0] * rs + sw[bj][0], c = acc[ai][bj][m][1] * rs + sw[bj][1];
; #pragma unroll
;                     for (int e = 0; e < 4; ++e) { a[e] = fmaxf(a[e], 0.f); a[e] *= a[e]; c[e] = fmaxf(c[e], 0.f); c[e] *= c[e]; }
;                     u32x4 w; w.x = cvt_pk_bf16(a[0], a[1]); w.y = cvt_pk_bf16(a[2], a[3]); w.z = cvt_pk_bf16(c[0], c[1]); w.w = cvt_pk_bf16(c[2], c[3]);
;                     *(u32x4*)(H + (size_t)row * DFF + col0 + 128 * bj) = w;
;                 }
	global_store_dwordx4 v[76:77], v[232:235], off offset:256
	ds_bpermute_b32 v236, v226, v56
	ds_bpermute_b32 v237, v226, v57
	ds_bpermute_b32 v238, v226, v58
	ds_bpermute_b32 v239, v226, v59
	v_pk_mul_f32 v[52:53], v[52:53], v[52:53]
	v_pk_fma_f32 v[46:47], v[46:47], v[64:65], v[122:123] op_sel_hi:[1,0,1]
	v_pk_mul_f32 v[56:57], v[44:45], v[44:45]
	v_max_f32_e32 v44, 0, v54
	v_max_f32_e32 v45, 0, v55
	v_pk_mul_f32 v[54:55], v[44:45], v[44:45]
	v_cvt_pk_bf16_f32 v44, v52, v53
	ds_read2_b32 v[52:53], v162 offset0:144 offset1:160
	v_max_f32_e32 v46, 0, v46
	v_max_f32_e32 v47, 0, v47
	v_pk_mul_f32 v[58:59], v[46:47], v[46:47]
	v_cvt_pk_bf16_f32 v45, v54, v55
	v_cvt_pk_bf16_f32 v46, v56, v57
	v_cvt_pk_bf16_f32 v47, v58, v59
	s_waitcnt lgkmcnt(0)
	global_store_dwordx4 v[60:61], v[236:239], off
	ds_bpermute_b32 v228, v226, v44
	ds_bpermute_b32 v229, v226, v45
	ds_bpermute_b32 v230, v226, v46
	ds_bpermute_b32 v231, v226, v47
	s_waitcnt lgkmcnt(0)
	v_pk_fma_f32 v[40:41], v[40:41], v[52:53], v[128:129] op_sel_hi:[1,0,1]
	v_pk_fma_f32 v[48:49], v[48:49], v[52:53], v[132:133] op_sel_hi:[1,0,1]
	v_add_u32_e32 v44, 0x90, v154
	v_ashrrev_i32_e32 v45, 31, v44
	v_pk_fma_f32 v[46:47], v[50:51], v[52:53], v[134:135] op_sel_hi:[1,0,1]
	v_pk_fma_f32 v[42:43], v[42:43], v[52:53], v[130:131] op_sel_hi:[1,0,1]
	v_max_f32_e32 v40, 0, v40
	v_max_f32_e32 v41, 0, v41
	v_lshlrev_b64 v[44:45], 13, v[44:45]
	v_max_f32_e32 v48, 0, v48
	v_max_f32_e32 v49, 0, v49
	v_pk_mul_f32 v[50:51], v[40:41], v[40:41]
	v_max_f32_e32 v40, 0, v46
	v_max_f32_e32 v42, 0, v42
	v_max_f32_e32 v41, 0, v47
	v_max_f32_e32 v43, 0, v43
	v_pk_mul_f32 v[48:49], v[48:49], v[48:49]
	v_pk_mul_f32 v[46:47], v[40:41], v[40:41]
	v_pk_mul_f32 v[54:55], v[42:43], v[42:43]
	v_lshl_add_u64 v[44:45], s[8:9], 0, v[44:45]
	v_pk_fma_f32 v[28:29], v[28:29], v[52:53], v[120:121] op_sel_hi:[1,0,1]
	v_cvt_pk_bf16_f32 v40, v48, v49
	v_cvt_pk_bf16_f32 v41, v46, v47
	v_cvt_pk_bf16_f32 v42, v50, v51
	v_cvt_pk_bf16_f32 v43, v54, v55
	v_lshl_add_u64 v[44:45], v[44:45], 0, v[136:137]
	v_pk_fma_f32 v[38:39], v[38:39], v[52:53], v[126:127] op_sel_hi:[1,0,1]
	v_pk_fma_f32 v[36:37], v[36:37], v[52:53], v[124:125] op_sel_hi:[1,0,1]
	v_pk_fma_f32 v[30:31], v[30:31], v[52:53], v[122:123] op_sel_hi:[1,0,1]
	v_max_f32_e32 v28, 0, v28
	v_max_f32_e32 v29, 0, v29
	s_waitcnt lgkmcnt(0)
	global_store_dwordx4 v[60:61], v[228:231], off offset:256
	ds_bpermute_b32 v232, v226, v40
	ds_bpermute_b32 v233, v226, v41
	ds_bpermute_b32 v234, v226, v42
	ds_bpermute_b32 v235, v226, v43
	v_max_f32_e32 v36, 0, v36
	v_max_f32_e32 v37, 0, v37
	v_pk_mul_f32 v[40:41], v[28:29], v[28:29]
	v_max_f32_e32 v28, 0, v38
	v_max_f32_e32 v30, 0, v30
	v_max_f32_e32 v29, 0, v39
	v_max_f32_e32 v31, 0, v31
	v_pk_mul_f32 v[36:37], v[36:37], v[36:37]
	v_pk_mul_f32 v[38:39], v[28:29], v[28:29]
	v_pk_mul_f32 v[42:43], v[30:31], v[30:31]
	v_cvt_pk_bf16_f32 v28, v36, v37
	v_cvt_pk_bf16_f32 v29, v38, v39
	v_cvt_pk_bf16_f32 v30, v40, v41
	v_cvt_pk_bf16_f32 v31, v42, v43
	s_waitcnt lgkmcnt(0)
	global_store_dwordx4 v[44:45], v[232:235], off
	ds_bpermute_b32 v236, v226, v28
	ds_bpermute_b32 v237, v226, v29
	ds_bpermute_b32 v238, v226, v30
	ds_bpermute_b32 v239, v226, v31
	v_pk_fma_f32 v[10:11], v[10:11], v[68:69], v[130:131] op_sel_hi:[1,0,1]
	v_max_f32_e32 v8, 0, v8
	v_mov_b32_e32 v30, v53
	v_add_u32_e32 v28, 0xa0, v154
	v_pk_fma_f32 v[24:25], v[24:25], v[30:31], v[128:129] op_sel_hi:[1,0,1]
	v_ashrrev_i32_e32 v29, 31, v28
	v_pk_fma_f32 v[34:35], v[34:35], v[30:31], v[134:135] op_sel_hi:[1,0,1]
	v_pk_fma_f32 v[32:33], v[32:33], v[30:31], v[132:133] op_sel_hi:[1,0,1]
	v_pk_fma_f32 v[26:27], v[26:27], v[30:31], v[130:131] op_sel_hi:[1,0,1]
	v_max_f32_e32 v24, 0, v24
	v_max_f32_e32 v25, 0, v25
	v_lshlrev_b64 v[28:29], 13, v[28:29]
	v_max_f32_e32 v32, 0, v32
	v_max_f32_e32 v33, 0, v33
	v_pk_mul_f32 v[36:37], v[24:25], v[24:25]
	v_max_f32_e32 v24, 0, v34
	v_max_f32_e32 v26, 0, v26
	v_max_f32_e32 v25, 0, v35
	v_max_f32_e32 v27, 0, v27
	v_pk_mul_f32 v[32:33], v[32:33], v[32:33]
	v_pk_mul_f32 v[34:35], v[24:25], v[24:25]
	v_pk_mul_f32 v[38:39], v[26:27], v[26:27]
	v_lshl_add_u64 v[28:29], s[8:9], 0, v[28:29]
	v_pk_fma_f32 v[12:13], v[12:13], v[30:31], v[120:121] op_sel_hi:[1,0,1]
	v_cvt_pk_bf16_f32 v24, v32, v33
	v_cvt_pk_bf16_f32 v25, v34, v35
	v_cvt_pk_bf16_f32 v26, v36, v37
	v_cvt_pk_bf16_f32 v27, v38, v39
	v_lshl_add_u64 v[28:29], v[28:29], 0, v[136:137]
	v_pk_fma_f32 v[22:23], v[22:23], v[30:31], v[126:127] op_sel_hi:[1,0,1]
	v_pk_fma_f32 v[20:21], v[20:21], v[30:31], v[124:125] op_sel_hi:[1,0,1]
	v_pk_fma_f32 v[14:15], v[14:15], v[30:31], v[122:123] op_sel_hi:[1,0,1]
	v_max_f32_e32 v12, 0, v12
	v_max_f32_e32 v13, 0, v13
	s_waitcnt lgkmcnt(0)
; __device__ __forceinline__ unsigned cvt_pk_bf16(float lo, float hi) { const cvt_f32x2_t v = {lo, hi}; const cvt_bf16x2_t b = __builtin_convertvector(v, cvt_bf16x2_t); return __builtin_bit_cast(unsigned, b); }
;     __device__ __forceinline__ void operator()(const f32x4 (&acc)[2][2][4][2], const Unit& u, int wr, int wc, int fr, int fq) const {
;     ...
;         for (int ai = 0; ai < 2; ++ai)
; #pragma unroll
;             for (int m = 0; m < 4; ++m) {
;                 const int row = u.pm * 256 + ai * 128 + wr * 64 + m * 16 + fr;
;                 const float rs = rsl[ai * 128 + wr * 64 + m * 16 + fr];
; #pragma unroll
;                 for (int bj = 0; bj < 2; ++bj) {
;                     f32x4 a = acc[ai][bj][m][0] * rs + sw[bj][0], c = acc[ai][bj][m][1] * rs + sw[bj][1];
; #pragma unroll
;                     for (int e = 0; e < 4; ++e) { a[e] = fmaxf(a[e], 0.f); a[e] *= a[e]; c[e] = fmaxf(c[e], 0.f); c[e] *= c[e]; }
;                     u32x4 w; w.x = cvt_pk_bf16(a[0], a[1]); w.y = cvt_pk_bf16(a[2], a[3]); w.z = cvt_pk_bf16(c[0], c[1]); w.w = cvt_pk_bf16(c[2], c[3]);
;                     *(u32x4*)(H + (size_t)row * DFF + col0 + 128 * bj) = w;
;                 }
	global_store_dwordx4 v[44:45], v[236:239], off offset:256
	ds_bpermute_b32 v228, v226, v24
	ds_bpermute_b32 v229, v226, v25
	ds_bpermute_b32 v230, v226, v26
	ds_bpermute_b32 v231, v226, v27
	v_max_f32_e32 v20, 0, v20
	v_max_f32_e32 v21, 0, v21
	v_pk_mul_f32 v[24:25], v[12:13], v[12:13]
	v_max_f32_e32 v12, 0, v22
	v_max_f32_e32 v14, 0, v14
	v_max_f32_e32 v13, 0, v23
	v_max_f32_e32 v15, 0, v15
	v_pk_mul_f32 v[20:21], v[20:21], v[20:21]
	v_pk_mul_f32 v[22:23], v[12:13], v[12:13]
	v_pk_mul_f32 v[26:27], v[14:15], v[14:15]
	v_cvt_pk_bf16_f32 v12, v20, v21
	v_cvt_pk_bf16_f32 v13, v22, v23
	v_cvt_pk_bf16_f32 v14, v24, v25
	v_cvt_pk_bf16_f32 v15, v26, v27
	s_waitcnt lgkmcnt(0)
	global_store_dwordx4 v[28:29], v[228:231], off
	ds_bpermute_b32 v232, v226, v12
	ds_bpermute_b32 v233, v226, v13
	ds_bpermute_b32 v234, v226, v14
	ds_bpermute_b32 v235, v226, v15
	v_max_f32_e32 v9, 0, v9
	v_max_f32_e32 v16, 0, v16
	v_add_u32_e32 v12, 0xb0, v154
	v_ashrrev_i32_e32 v13, 31, v12
	v_pk_fma_f32 v[14:15], v[18:19], v[68:69], v[134:135] op_sel_hi:[1,0,1]
	v_lshlrev_b64 v[12:13], 13, v[12:13]
	v_max_f32_e32 v17, 0, v17
	v_pk_mul_f32 v[18:19], v[8:9], v[8:9]
	v_max_f32_e32 v8, 0, v14
	v_max_f32_e32 v10, 0, v10
	v_max_f32_e32 v9, 0, v15
	v_max_f32_e32 v11, 0, v11
	v_pk_mul_f32 v[16:17], v[16:17], v[16:17]
	v_pk_mul_f32 v[14:15], v[8:9], v[8:9]
	v_pk_mul_f32 v[20:21], v[10:11], v[10:11]
	v_lshl_add_u64 v[12:13], s[8:9], 0, v[12:13]
	v_pk_fma_f32 v[0:1], v[0:1], v[68:69], v[120:121] op_sel_hi:[1,0,1]
	v_cvt_pk_bf16_f32 v8, v16, v17
	v_cvt_pk_bf16_f32 v9, v14, v15
	v_cvt_pk_bf16_f32 v10, v18, v19
	v_cvt_pk_bf16_f32 v11, v20, v21
	v_lshl_add_u64 v[12:13], v[12:13], 0, v[136:137]
	v_pk_fma_f32 v[6:7], v[6:7], v[68:69], v[126:127] op_sel_hi:[1,0,1]
	v_pk_fma_f32 v[4:5], v[4:5], v[68:69], v[124:125] op_sel_hi:[1,0,1]
	v_pk_fma_f32 v[2:3], v[2:3], v[68:69], v[122:123] op_sel_hi:[1,0,1]
	v_max_f32_e32 v0, 0, v0
	v_max_f32_e32 v1, 0, v1
	s_waitcnt lgkmcnt(0)
	global_store_dwordx4 v[28:29], v[232:235], off offset:256
	ds_bpermute_b32 v236, v226, v8
	ds_bpermute_b32 v237, v226, v9
	ds_bpermute_b32 v238, v226, v10
	ds_bpermute_b32 v239, v226, v11
	v_max_f32_e32 v4, 0, v4
	v_max_f32_e32 v5, 0, v5
	v_pk_mul_f32 v[8:9], v[0:1], v[0:1]
	v_max_f32_e32 v0, 0, v6
	v_max_f32_e32 v2, 0, v2
	v_max_f32_e32 v1, 0, v7
	v_max_f32_e32 v3, 0, v3
	v_pk_mul_f32 v[4:5], v[4:5], v[4:5]
	v_pk_mul_f32 v[6:7], v[0:1], v[0:1]
	v_pk_mul_f32 v[10:11], v[2:3], v[2:3]
	v_cvt_pk_bf16_f32 v0, v4, v5
	v_cvt_pk_bf16_f32 v1, v6, v7
	v_cvt_pk_bf16_f32 v2, v8, v9
	v_cvt_pk_bf16_f32 v3, v10, v11
	s_waitcnt lgkmcnt(0)
	global_store_dwordx4 v[12:13], v[236:239], off
	ds_bpermute_b32 v228, v226, v0
	ds_bpermute_b32 v229, v226, v1
	ds_bpermute_b32 v230, v226, v2
	ds_bpermute_b32 v231, v226, v3
	s_waitcnt lgkmcnt(0)
	global_store_dwordx4 v[12:13], v[228:231], off offset:256
	s_cbranch_vccnz .LBB0_279
	v_readlane_b32 s4, v255, 46
	v_readlane_b32 s5, v255, 47
	s_andn2_b64 vcc, exec, s[4:5]
	s_cbranch_vccnz .LBB0_278
	s_barrier
	s_branch .LBB0_278

; #define LAS __attribute__((address_space(3)))
; __device__ __forceinline__ unsigned cvt_pk_bf16(float lo, float hi) { const cvt_f32x2_t v = {lo, hi}; const cvt_bf16x2_t b = __builtin_convertvector(v, cvt_bf16x2_t); return __builtin_bit_cast(unsigned, b); }
; __device__ __forceinline__ float sq4(f32x4 v) { return (v[0] * v[0] + v[1] * v[1]) + (v[2] * v[2] + v[3] * v[3]); }
;     __device__ __forceinline__ void operator()(const f32x4 (&acc)[2][2][4][2], const Unit& u, int wr, int wc, int fr, int fq) const {
;     ...
;             for (int m = 0; m < 4; ++m) { const size_t off = (size_t)(u.pm * 256 + ai * 128 + wr * 64 + m * 16 + fr) * DM + col0;
; #pragma unroll
;                 for (int bj = 0; bj < 2; ++bj)
; #pragma unroll
;                     for (int n = 0; n < 2; ++n) xr[m][bj][n] = *(const f32x4*)(xin + off + 128 * bj + 4 * n); }
;             asm volatile("" ::: "memory");
; #pragma unroll
;             for (int m = 0; m < 4; ++m) {
;                 const int row = u.pm * 256 + ai * 128 + wr * 64 + m * 16 + fr;
;                 const size_t off = (size_t)row * DM + col0;
;                 float ss = 0.f;
; #pragma unroll
;                 for (int bj = 0; bj < 2; ++bj) {
;                     const f32x4 xo0 = xr[m][bj][0] + *(const LAS f32x4*)(gtp + 128 * bj) * acc[ai][bj][m][0], xo1 = xr[m][bj][1] + *(const LAS f32x4*)(gtp + 128 * bj + 4) * acc[ai][bj][m][1];
;                     *(f32x4*)(xout + off + 128 * bj) = xo0; *(f32x4*)(xout + off + 128 * bj + 4) = xo1;
;                     if (gmn) { ss += sq4(xo0) + sq4(xo1); const f32x4 a = xo0 * *(const LAS f32x4*)(gmp + 128 * bj), c = xo1 * *(const LAS f32x4*)(gmp + 128 * bj + 4);
;                         u32x4 w; w.x = cvt_pk_bf16(a[0], a[1]); w.y = cvt_pk_bf16(a[2], a[3]); w.z = cvt_pk_bf16(c[0], c[1]); w.w = cvt_pk_bf16(c[2], c[3]); *(u32x4*)(AX + off + 128 * bj) = w; }
;                 }
;                 if (gmn) { ss += __shfl_xor(ss, 16); ss += __shfl_xor(ss, 32); if (fq == 0) statx[(size_t)row * 16 + u.pn * 4 + wc] = ss; }
.LBB0_347:
	v_add_u32_e32 v134, 0x80, v226
	v_ashrrev_i32_e32 v135, 31, v134
	s_waitcnt lgkmcnt(0)
	v_lshlrev_b64 v[64:65], 12, v[134:135]
	v_add_u32_e32 v132, 0x90, v226
	v_lshl_add_u64 v[64:65], v[228:229], 0, v[64:65]
	v_ashrrev_i32_e32 v133, 31, v132
	global_load_dwordx4 v[136:139], v[64:65], off offset:16
	global_load_dwordx4 v[140:143], v[64:65], off
	global_load_dwordx4 v[120:123], v[64:65], off offset:528
	global_load_dwordx4 v[124:127], v[64:65], off offset:512
	v_lshlrev_b64 v[64:65], 12, v[132:133]
	v_add_u32_e32 v130, 0xa0, v226
	v_lshl_add_u64 v[64:65], v[228:229], 0, v[64:65]
	v_ashrrev_i32_e32 v131, 31, v130
	global_load_dwordx4 v[112:115], v[64:65], off offset:16
	global_load_dwordx4 v[116:119], v[64:65], off
	global_load_dwordx4 v[104:107], v[64:65], off offset:528
	global_load_dwordx4 v[108:111], v[64:65], off offset:512
	v_lshlrev_b64 v[64:65], 12, v[130:131]
	v_add_u32_e32 v128, 0xb0, v226
	v_lshl_add_u64 v[64:65], v[228:229], 0, v[64:65]
	v_ashrrev_i32_e32 v129, 31, v128
	global_load_dwordx4 v[96:99], v[64:65], off offset:16
	global_load_dwordx4 v[100:103], v[64:65], off
	global_load_dwordx4 v[88:91], v[64:65], off offset:528
	global_load_dwordx4 v[92:95], v[64:65], off offset:512
	v_lshlrev_b64 v[64:65], 12, v[128:129]
	v_lshl_add_u64 v[68:69], v[228:229], 0, v[64:65]
	global_load_dwordx4 v[72:75], v[68:69], off offset:16
	global_load_dwordx4 v[80:83], v[68:69], off
	global_load_dwordx4 v[64:67], v[68:69], off offset:528
	s_nop 0
	global_load_dwordx4 v[68:71], v[68:69], off offset:512
	v_lshlrev_b64 v[76:77], 10, v[134:135]
	v_lshl_add_u64 v[144:145], v[76:77], 0, v[224:225]
	ds_read_b128 v[84:87], v249
	ds_read_b128 v[76:79], v249 offset:16
	s_and_b64 vcc, exec, s[46:47]
	s_waitcnt vmcnt(0) lgkmcnt(0)
	v_pk_fma_f32 v[58:59], v[58:59], v[78:79], v[138:139]
	s_waitcnt vmcnt(14)
	v_pk_fma_f32 v[62:63], v[62:63], v[86:87], v[142:143]
	v_pk_fma_f32 v[60:61], v[60:61], v[84:85], v[140:141]
	v_pk_fma_f32 v[56:57], v[56:57], v[76:77], v[136:137]
	v_lshl_add_u64 v[136:137], v[144:145], 2, s[6:7]
	v_lshl_add_u32 v136, v144, 2, v246
	v_mov_b32_e32 v140, 0
	v_lshl_add_u64 v[138:139], v[144:145], 1, s[16:17]
	v_lshl_add_u64 v[138:139], v[204:205], 0, v[138:139]
	ds_write_b128 v208, v[60:63]
	ds_write_b128 v208, v[56:59] offset:16
	ds_read_b128 v[216:219], v210
	ds_read_b128 v[220:223], v210 offset:1152
	s_waitcnt lgkmcnt(0)
	global_store_dwordx4 v136, v[216:219], s[6:7]
	global_store_dwordx4 v136, v[220:223], s[100:101]
	s_cbranch_vccnz .LBB0_349
	v_mov_b32_e32 v142, v61
	v_mov_b32_e32 v143, v57
	v_mov_b32_e32 v140, v60
	v_mov_b32_e32 v141, v56
	v_pk_mul_f32 v[142:143], v[142:143], v[142:143]
	v_mov_b32_e32 v144, v63
	v_mov_b32_e32 v145, v59
	v_pk_fma_f32 v[140:141], v[140:141], v[140:141], v[142:143]
	v_mov_b32_e32 v142, v62
	v_mov_b32_e32 v143, v58
	v_pk_mul_f32 v[144:145], v[144:145], v[144:145]
	s_nop 0
	v_pk_fma_f32 v[142:143], v[142:143], v[142:143], v[144:145]
	s_nop 0
	v_pk_add_f32 v[140:141], v[140:141], v[142:143]
	ds_read_b128 v[142:145], v192
	ds_read_b128 v[146:149], v192 offset:16
	v_add_f32_e32 v140, v140, v141
	s_waitcnt lgkmcnt(1)
	v_pk_mul_f32 v[62:63], v[62:63], v[144:145]
	v_pk_mul_f32 v[60:61], v[60:61], v[142:143]
	s_waitcnt lgkmcnt(0)
	v_pk_mul_f32 v[142:143], v[58:59], v[148:149]
	v_pk_mul_f32 v[58:59], v[56:57], v[146:147]
	v_cvt_pk_bf16_f32 v56, v60, v61
	v_cvt_pk_bf16_f32 v57, v62, v63
	v_cvt_pk_bf16_f32 v58, v58, v59
	v_cvt_pk_bf16_f32 v59, v142, v143
	ds_bpermute_b32 v56, v206, v56
	ds_bpermute_b32 v57, v206, v57
	ds_bpermute_b32 v58, v206, v58
	ds_bpermute_b32 v59, v206, v59
	s_waitcnt lgkmcnt(0)
	global_store_dwordx4 v[138:139], v[56:59], off
